# barrier-shadow work: the one-item-per-wave weight conversion of the four-tile CUs moved from the end of P1 into the latency of the P2->P3 grid barrier (waves 1-7)
# baseline (speedup 1.0000x reference)
.LBB0_14:
	s_or_b64 exec, exec, s[0:1]
	v_readlane_b32 s0, v252, 0
	s_ashr_i32 s34, s2, 6
	s_lshl_b32 s0, s0, 3
	s_add_i32 s12, s34, s0
	v_and_b32_e32 v1, 63, v34
	s_lshl_b32 s16, s3, 3
	s_mov_b32 s8, s7
	s_mov_b32 s13, s6
	s_mov_b32 s7, s34
	s_mov_b32 s62, -1
	s_mov_b32 s36, 0
	s_mov_b32 s70, s12
	s_mov_b32 s71, s16
	s_movk_i32 s9, 0x2520
	s_branch .Ltail_go

.LBB0_174:
	s_mov_b32 s36, 0
	s_waitcnt vmcnt(0)
	s_mov_b32 s53, 0x2aaaaaab
	v_readlane_b32 s62, v254, 50
	s_barrier
	v_readlane_b32 s63, v254, 51
	s_cmp_ge_u32 s62, 3
	s_cbranch_scc1 .Ltail_end
	s_movk_i32 s4, 0x3c0

.Ltail_mod_done:
	v_readlane_b32 s5, v252, 0
	s_sub_u32 s6, s3, s4
	v_readfirstlane_b32 s7, v194
	s_lshr_b32 s7, s7, 6
	s_lshl_b32 s71, s6, 3
	s_mul_i32 s9, s4, 7
	s_sub_u32 s9, 0x2520, s9
	s_cmp_lt_u32 s5, s4
	s_cbranch_scc1 .Ltail_end
	s_sub_u32 s5, s5, s4
	s_lshl_b32 s5, s5, 3
	s_add_u32 s70, s5, s7
	s_branch .Ltail_go

.Ltail_end:
	s_cmp_eq_u32 s62, -1
	s_cbranch_scc1 .Lp0_ret
	s_cmp_eq_u32 s36, 0x51
	s_cbranch_scc1 .Lb2_ret

.Lb2_conv:
	s_mov_b64 exec, s[4:5]
	s_cmp_ge_u32 s62, 3
	s_cbranch_scc1 .Lb2_skip
	s_movk_i32 s4, 0x3c0

.Lb2_mod_done:
	v_readlane_b32 s5, v252, 0
	s_cmp_lt_u32 s5, s4
	s_cbranch_scc0 .Lb2_skip
	v_readfirstlane_b32 s7, v194
	s_lshr_b32 s7, s7, 6
	s_mul_i32 s9, s4, 7
	s_sub_u32 s9, 0x2520, s9
	s_mul_i32 s5, s5, 7
	s_add_u32 s70, s5, s7
	s_sub_u32 s70, s70, 1
	s_add_u32 s70, s70, s9
	s_movk_i32 s9, 0x2520
	s_movk_i32 s71, 0x4000
	s_movk_i32 s36, 0x51
	s_branch .Ltail_go
.Lb2_ret:
	s_mov_b32 s36, 0
.Lb2_skip:
	s_mov_b64 s[4:5], -1
	s_branch .LBB0_303
